# v30 + nt cache hint on FFN-in ACT stores (keeps residual stream in last-level cache)
# speedup vs baseline: 1.0106x; 1.0093x over previous
.LBB0_183:
	v_mul_f32_e32 v159, 0xbfb8aa3b, v124
	v_exp_f32_e32 v159, v159
	v_lshl_or_b32 v160, s65, 7, v156
	v_lshl_add_u32 v158, s66, 8, v140
	v_ashrrev_i32_e32 v161, 31, v160
	v_add_f32_e32 v159, 1.0, v159
	v_rcp_f32_e32 v159, v159
	v_mov_b64_e32 v[138:139], s[0:1]
	v_mad_i64_i32 v[162:163], s[28:29], v158, s91, v[138:139]
	v_mul_f32_e32 v124, v124, v159
	v_mul_f32_e32 v120, v124, v120
	v_mul_f32_e32 v124, 0xbfb8aa3b, v116
	v_exp_f32_e32 v124, v124
	s_mov_b64 s[50:51], -1
	s_andn2_b64 vcc, exec, s[36:37]
	v_add_f32_e32 v124, 1.0, v124
	v_rcp_f32_e32 v124, v124
	s_nop 0
	v_mul_f32_e32 v116, v116, v124
	v_mul_f32_e32 v116, v116, v112
	v_mul_f32_e32 v112, 0xbfb8aa3b, v125
	v_exp_f32_e32 v112, v112
	s_nop 0
	v_add_f32_e32 v112, 1.0, v112
	v_rcp_f32_e32 v112, v112
	s_nop 0
	v_mul_f32_e32 v112, v125, v112
	v_mul_f32_e32 v121, v112, v121
	v_mul_f32_e32 v112, 0xbfb8aa3b, v117
	v_exp_f32_e32 v112, v112
	s_nop 0
	v_add_f32_e32 v112, 1.0, v112
	v_rcp_f32_e32 v112, v112
	s_nop 0
	v_mul_f32_e32 v112, v117, v112
	v_mul_f32_e32 v117, v112, v113
	v_mul_f32_e32 v112, 0xbfb8aa3b, v126
	v_exp_f32_e32 v112, v112
	s_nop 0
	v_add_f32_e32 v112, 1.0, v112
	v_rcp_f32_e32 v112, v112
	s_nop 0
	v_mul_f32_e32 v112, v126, v112
	v_mul_f32_e32 v122, v112, v122
	v_mul_f32_e32 v112, 0xbfb8aa3b, v118
	v_exp_f32_e32 v112, v112
	s_nop 0
	v_add_f32_e32 v112, 1.0, v112
	v_rcp_f32_e32 v112, v112
	s_nop 0
	v_mul_f32_e32 v112, v118, v112
	v_mul_f32_e32 v124, v112, v114
	v_mul_f32_e32 v112, 0xbfb8aa3b, v127
	v_exp_f32_e32 v112, v112
	v_cvt_pk_bf16_f32 v114, v120, v121
	s_nop 0
	v_add_f32_e32 v112, 1.0, v112
	v_rcp_f32_e32 v112, v112
	s_nop 0
	v_mul_f32_e32 v112, v127, v112
	v_mul_f32_e32 v123, v112, v123
	v_mul_f32_e32 v112, 0xbfb8aa3b, v119
	v_exp_f32_e32 v112, v112
	s_nop 0
	v_add_f32_e32 v112, 1.0, v112
	v_rcp_f32_e32 v112, v112
	s_nop 0
	v_mul_f32_e32 v112, v119, v112
	v_mul_f32_e32 v125, v112, v115
	v_lshlrev_b64 v[112:113], 1, v[160:161]
	v_cvt_pk_bf16_f32 v115, v122, v123
	v_cvt_pk_bf16_f32 v116, v116, v117
	v_lshl_add_u64 v[118:119], v[162:163], 0, v[112:113]
	v_cvt_pk_bf16_f32 v117, v124, v125
	s_nop 0
	global_store_dwordx4 v[118:119], v[114:117], off sc1 nt
	s_nop 1
	v_mul_f32_e32 v116, 0xbfb8aa3b, v108
	v_exp_f32_e32 v116, v116
	v_or_b32_e32 v114, 16, v158
	v_mad_i64_i32 v[114:115], s[28:29], v114, s91, v[138:139]
	v_add_f32_e32 v116, 1.0, v116
	v_rcp_f32_e32 v116, v116
	s_nop 0
	v_mul_f32_e32 v108, v108, v116
	v_mul_f32_e32 v104, v108, v104
	v_mul_f32_e32 v108, 0xbfb8aa3b, v100
	v_exp_f32_e32 v108, v108
	s_nop 0
	v_add_f32_e32 v108, 1.0, v108
	v_rcp_f32_e32 v108, v108
	s_nop 0
	v_mul_f32_e32 v100, v100, v108
	v_mul_f32_e32 v108, v100, v96
	v_mul_f32_e32 v96, 0xbfb8aa3b, v109
	v_mul_f32_e32 v100, 0xbfb8aa3b, v101
	v_exp_f32_e32 v96, v96
	v_exp_f32_e32 v100, v100
	v_add_f32_e32 v96, 1.0, v96
	v_add_f32_e32 v100, 1.0, v100
	v_rcp_f32_e32 v96, v96
	v_rcp_f32_e32 v100, v100
	v_mul_f32_e32 v96, v109, v96
	v_mul_f32_e32 v100, v101, v100
	v_mul_f32_e32 v96, v96, v105
	v_mul_f32_e32 v105, v100, v97
	v_mul_f32_e32 v100, 0xbfb8aa3b, v102
	v_exp_f32_e32 v100, v100
	v_mul_f32_e32 v97, 0xbfb8aa3b, v110
	v_exp_f32_e32 v97, v97
	v_cvt_pk_bf16_f32 v96, v104, v96
	v_add_f32_e32 v100, 1.0, v100
	v_rcp_f32_e32 v100, v100
	v_add_f32_e32 v97, 1.0, v97
	v_rcp_f32_e32 v97, v97
	v_mul_f32_e32 v100, v102, v100
	v_mul_f32_e32 v102, v100, v98
	v_mul_f32_e32 v98, 0xbfb8aa3b, v111
	v_exp_f32_e32 v98, v98
	v_mul_f32_e32 v100, 0xbfb8aa3b, v103
	v_exp_f32_e32 v100, v100
	v_mul_f32_e32 v97, v110, v97
	v_add_f32_e32 v98, 1.0, v98
	v_rcp_f32_e32 v98, v98
	v_add_f32_e32 v100, 1.0, v100
	v_rcp_f32_e32 v100, v100
	v_mul_f32_e32 v97, v97, v106
	v_mul_f32_e32 v98, v111, v98
	v_mul_f32_e32 v98, v98, v107
	v_mul_f32_e32 v100, v103, v100
	v_mul_f32_e32 v99, v100, v99
	v_cvt_pk_bf16_f32 v97, v97, v98
	v_cvt_pk_bf16_f32 v98, v108, v105
	v_lshl_add_u64 v[100:101], v[114:115], 0, v[112:113]
	v_cvt_pk_bf16_f32 v99, v102, v99
	s_nop 0
	global_store_dwordx4 v[100:101], v[96:99], off sc1 nt
	s_nop 1
	v_mul_f32_e32 v98, 0xbfb8aa3b, v92
	v_exp_f32_e32 v98, v98
	v_or_b32_e32 v96, 32, v158
	v_mad_i64_i32 v[96:97], s[28:29], v96, s91, v[138:139]
	v_add_f32_e32 v98, 1.0, v98
	v_rcp_f32_e32 v98, v98
	s_nop 0
	v_mul_f32_e32 v92, v92, v98
	v_mul_f32_e32 v88, v92, v88
	v_mul_f32_e32 v92, 0xbfb8aa3b, v84
	v_exp_f32_e32 v92, v92
	s_nop 0
	v_add_f32_e32 v92, 1.0, v92
	v_rcp_f32_e32 v92, v92
	s_nop 0
	v_mul_f32_e32 v84, v84, v92
	v_mul_f32_e32 v92, v84, v80
	v_mul_f32_e32 v80, 0xbfb8aa3b, v93
	v_mul_f32_e32 v84, 0xbfb8aa3b, v85
	v_exp_f32_e32 v80, v80
	v_exp_f32_e32 v84, v84
	v_add_f32_e32 v80, 1.0, v80
	v_add_f32_e32 v84, 1.0, v84
	v_rcp_f32_e32 v80, v80
	v_rcp_f32_e32 v84, v84
	v_mul_f32_e32 v80, v93, v80
	v_mul_f32_e32 v84, v85, v84
	v_mul_f32_e32 v80, v80, v89
	v_mul_f32_e32 v89, v84, v81
	v_mul_f32_e32 v84, 0xbfb8aa3b, v86
	v_exp_f32_e32 v84, v84
	v_mul_f32_e32 v81, 0xbfb8aa3b, v94
	v_exp_f32_e32 v81, v81
	v_cvt_pk_bf16_f32 v80, v88, v80
	v_add_f32_e32 v84, 1.0, v84
	v_rcp_f32_e32 v84, v84
	v_add_f32_e32 v81, 1.0, v81
	v_rcp_f32_e32 v81, v81
	v_mul_f32_e32 v84, v86, v84
	v_mul_f32_e32 v86, v84, v82
	v_mul_f32_e32 v82, 0xbfb8aa3b, v95
	v_exp_f32_e32 v82, v82
	v_mul_f32_e32 v84, 0xbfb8aa3b, v87
	v_exp_f32_e32 v84, v84
	v_mul_f32_e32 v81, v94, v81
	v_add_f32_e32 v82, 1.0, v82
	v_rcp_f32_e32 v82, v82
	v_add_f32_e32 v84, 1.0, v84
	v_rcp_f32_e32 v84, v84
	v_mul_f32_e32 v81, v81, v90
	v_mul_f32_e32 v82, v95, v82
	v_mul_f32_e32 v82, v82, v91
	v_mul_f32_e32 v84, v87, v84
	v_mul_f32_e32 v83, v84, v83
	v_cvt_pk_bf16_f32 v81, v81, v82
	v_cvt_pk_bf16_f32 v82, v92, v89
	v_lshl_add_u64 v[84:85], v[96:97], 0, v[112:113]
	v_cvt_pk_bf16_f32 v83, v86, v83
	s_nop 0
	global_store_dwordx4 v[84:85], v[80:83], off sc1 nt
	s_nop 1
	v_mul_f32_e32 v82, 0xbfb8aa3b, v76
	v_exp_f32_e32 v82, v82
	v_or_b32_e32 v80, 48, v158
	v_mad_i64_i32 v[80:81], s[28:29], v80, s91, v[138:139]
	v_add_f32_e32 v82, 1.0, v82
	v_rcp_f32_e32 v82, v82
	s_nop 0
	v_mul_f32_e32 v76, v76, v82
	v_mul_f32_e32 v72, v76, v72
	v_mul_f32_e32 v76, 0xbfb8aa3b, v68
	v_exp_f32_e32 v76, v76
	s_nop 0
	v_add_f32_e32 v76, 1.0, v76
	v_rcp_f32_e32 v76, v76
	s_nop 0
	v_mul_f32_e32 v68, v68, v76
	v_mul_f32_e32 v76, v68, v64
	v_mul_f32_e32 v64, 0xbfb8aa3b, v77
	v_mul_f32_e32 v68, 0xbfb8aa3b, v69
	v_exp_f32_e32 v64, v64
	v_exp_f32_e32 v68, v68
	v_add_f32_e32 v64, 1.0, v64
	v_add_f32_e32 v68, 1.0, v68
	v_rcp_f32_e32 v64, v64
	v_rcp_f32_e32 v68, v68
	v_mul_f32_e32 v64, v77, v64
	v_mul_f32_e32 v68, v69, v68
	v_mul_f32_e32 v64, v64, v73
	v_mul_f32_e32 v73, v68, v65
	v_mul_f32_e32 v68, 0xbfb8aa3b, v70
	v_exp_f32_e32 v68, v68
	v_mul_f32_e32 v65, 0xbfb8aa3b, v78
	v_exp_f32_e32 v65, v65
	v_cvt_pk_bf16_f32 v64, v72, v64
	v_add_f32_e32 v68, 1.0, v68
	v_rcp_f32_e32 v68, v68
	v_add_f32_e32 v65, 1.0, v65
	v_rcp_f32_e32 v65, v65
	v_mul_f32_e32 v68, v70, v68
	v_mul_f32_e32 v70, v68, v66
	v_mul_f32_e32 v66, 0xbfb8aa3b, v79
	v_exp_f32_e32 v66, v66
	v_mul_f32_e32 v68, 0xbfb8aa3b, v71
	v_exp_f32_e32 v68, v68
	v_mul_f32_e32 v65, v78, v65
	v_add_f32_e32 v66, 1.0, v66
	v_rcp_f32_e32 v66, v66
	v_add_f32_e32 v68, 1.0, v68
	v_rcp_f32_e32 v68, v68
	v_mul_f32_e32 v65, v65, v74
	v_mul_f32_e32 v66, v79, v66
	v_mul_f32_e32 v66, v66, v75
	v_mul_f32_e32 v68, v71, v68
	v_mul_f32_e32 v67, v68, v67
	v_cvt_pk_bf16_f32 v65, v65, v66
	v_cvt_pk_bf16_f32 v66, v76, v73
	v_lshl_add_u64 v[68:69], v[80:81], 0, v[112:113]
	v_cvt_pk_bf16_f32 v67, v70, v67
	s_nop 0
	global_store_dwordx4 v[68:69], v[64:67], off sc1 nt
	s_nop 1
	v_mul_f32_e32 v66, 0xbfb8aa3b, v60
	v_exp_f32_e32 v66, v66
	v_add_u32_e32 v64, 0x80, v158
	v_mad_i64_i32 v[64:65], s[28:29], v64, s91, v[138:139]
	v_add_f32_e32 v66, 1.0, v66
	v_rcp_f32_e32 v66, v66
	s_nop 0
	v_mul_f32_e32 v60, v60, v66
	v_mul_f32_e32 v56, v60, v56
	v_mul_f32_e32 v60, 0xbfb8aa3b, v52
	v_exp_f32_e32 v60, v60
	s_nop 0
	v_add_f32_e32 v60, 1.0, v60
	v_rcp_f32_e32 v60, v60
	s_nop 0
	v_mul_f32_e32 v52, v52, v60
	v_mul_f32_e32 v60, v52, v48
	v_mul_f32_e32 v48, 0xbfb8aa3b, v61
	v_mul_f32_e32 v52, 0xbfb8aa3b, v53
	v_exp_f32_e32 v48, v48
	v_exp_f32_e32 v52, v52
	v_add_f32_e32 v48, 1.0, v48
	v_add_f32_e32 v52, 1.0, v52
	v_rcp_f32_e32 v48, v48
	v_rcp_f32_e32 v52, v52
	v_mul_f32_e32 v48, v61, v48
	v_mul_f32_e32 v52, v53, v52
	v_mul_f32_e32 v48, v48, v57
	v_mul_f32_e32 v57, v52, v49
	v_mul_f32_e32 v52, 0xbfb8aa3b, v54
	v_exp_f32_e32 v52, v52
	v_mul_f32_e32 v49, 0xbfb8aa3b, v62
	v_exp_f32_e32 v49, v49
	v_cvt_pk_bf16_f32 v48, v56, v48
	v_add_f32_e32 v52, 1.0, v52
	v_rcp_f32_e32 v52, v52
	v_add_f32_e32 v49, 1.0, v49
	v_rcp_f32_e32 v49, v49
	v_mul_f32_e32 v52, v54, v52
	v_mul_f32_e32 v54, v52, v50
	v_mul_f32_e32 v50, 0xbfb8aa3b, v63
	v_exp_f32_e32 v50, v50
	v_mul_f32_e32 v52, 0xbfb8aa3b, v55
	v_exp_f32_e32 v52, v52
	v_mul_f32_e32 v49, v62, v49
	v_add_f32_e32 v50, 1.0, v50
	v_rcp_f32_e32 v50, v50
	v_add_f32_e32 v52, 1.0, v52
	v_rcp_f32_e32 v52, v52
	v_mul_f32_e32 v49, v49, v58
	v_mul_f32_e32 v50, v63, v50
	v_mul_f32_e32 v50, v50, v59
	v_mul_f32_e32 v52, v55, v52
	v_mul_f32_e32 v51, v52, v51
	v_cvt_pk_bf16_f32 v49, v49, v50
	v_cvt_pk_bf16_f32 v50, v60, v57
	v_lshl_add_u64 v[52:53], v[64:65], 0, v[112:113]
	v_cvt_pk_bf16_f32 v51, v54, v51
	s_nop 0
	global_store_dwordx4 v[52:53], v[48:51], off sc1 nt
	s_nop 1
	v_mul_f32_e32 v50, 0xbfb8aa3b, v44
	v_exp_f32_e32 v50, v50
	v_add_u32_e32 v48, 0x90, v158
	v_mad_i64_i32 v[48:49], s[28:29], v48, s91, v[138:139]
	v_add_f32_e32 v50, 1.0, v50
	v_rcp_f32_e32 v50, v50
	s_nop 0
	v_mul_f32_e32 v44, v44, v50
	v_mul_f32_e32 v40, v44, v40
	v_mul_f32_e32 v44, 0xbfb8aa3b, v36
	v_exp_f32_e32 v44, v44
	s_nop 0
	v_add_f32_e32 v44, 1.0, v44
	v_rcp_f32_e32 v44, v44
	s_nop 0
	v_mul_f32_e32 v36, v36, v44
	v_mul_f32_e32 v44, v36, v32
	v_mul_f32_e32 v32, 0xbfb8aa3b, v45
	v_mul_f32_e32 v36, 0xbfb8aa3b, v37
	v_exp_f32_e32 v32, v32
	v_exp_f32_e32 v36, v36
	v_add_f32_e32 v32, 1.0, v32
	v_add_f32_e32 v36, 1.0, v36
	v_rcp_f32_e32 v32, v32
	v_rcp_f32_e32 v36, v36
	v_mul_f32_e32 v32, v45, v32
	v_mul_f32_e32 v36, v37, v36
	v_mul_f32_e32 v32, v32, v41
	v_mul_f32_e32 v41, v36, v33
	v_mul_f32_e32 v36, 0xbfb8aa3b, v38
	v_exp_f32_e32 v36, v36
	v_mul_f32_e32 v33, 0xbfb8aa3b, v46
	v_exp_f32_e32 v33, v33
	v_cvt_pk_bf16_f32 v32, v40, v32
	v_add_f32_e32 v36, 1.0, v36
	v_rcp_f32_e32 v36, v36
	v_add_f32_e32 v33, 1.0, v33
	v_rcp_f32_e32 v33, v33
	v_mul_f32_e32 v36, v38, v36
	v_mul_f32_e32 v38, v36, v34
	v_mul_f32_e32 v34, 0xbfb8aa3b, v47
	v_exp_f32_e32 v34, v34
	v_mul_f32_e32 v36, 0xbfb8aa3b, v39
	v_exp_f32_e32 v36, v36
	v_mul_f32_e32 v33, v46, v33
	v_add_f32_e32 v34, 1.0, v34
	v_rcp_f32_e32 v34, v34
	v_add_f32_e32 v36, 1.0, v36
	v_rcp_f32_e32 v36, v36
	v_mul_f32_e32 v33, v33, v42
	v_mul_f32_e32 v34, v47, v34
	v_mul_f32_e32 v34, v34, v43
	v_mul_f32_e32 v36, v39, v36
	v_mul_f32_e32 v35, v36, v35
	v_cvt_pk_bf16_f32 v33, v33, v34
	v_cvt_pk_bf16_f32 v34, v44, v41
	v_lshl_add_u64 v[36:37], v[48:49], 0, v[112:113]
	v_cvt_pk_bf16_f32 v35, v38, v35
	s_nop 0
	global_store_dwordx4 v[36:37], v[32:35], off sc1 nt
	s_nop 1
	v_mul_f32_e32 v34, 0xbfb8aa3b, v28
	v_exp_f32_e32 v34, v34
	v_add_u32_e32 v32, 0xa0, v158
	v_mad_i64_i32 v[32:33], s[28:29], v32, s91, v[138:139]
	v_add_f32_e32 v34, 1.0, v34
	v_rcp_f32_e32 v34, v34
	s_nop 0
	v_mul_f32_e32 v28, v28, v34
	v_mul_f32_e32 v24, v28, v24
	v_mul_f32_e32 v28, 0xbfb8aa3b, v20
	v_exp_f32_e32 v28, v28
	s_nop 0
	v_add_f32_e32 v28, 1.0, v28
	v_rcp_f32_e32 v28, v28
	s_nop 0
	v_mul_f32_e32 v20, v20, v28
	v_mul_f32_e32 v28, v20, v16
	v_mul_f32_e32 v16, 0xbfb8aa3b, v29
	v_mul_f32_e32 v20, 0xbfb8aa3b, v21
	v_exp_f32_e32 v16, v16
	v_exp_f32_e32 v20, v20
	v_add_f32_e32 v16, 1.0, v16
	v_add_f32_e32 v20, 1.0, v20
	v_rcp_f32_e32 v16, v16
	v_rcp_f32_e32 v20, v20
	v_mul_f32_e32 v16, v29, v16
	v_mul_f32_e32 v20, v21, v20
	v_mul_f32_e32 v16, v16, v25
	v_mul_f32_e32 v25, v20, v17
	v_mul_f32_e32 v20, 0xbfb8aa3b, v22
	v_exp_f32_e32 v20, v20
	v_mul_f32_e32 v17, 0xbfb8aa3b, v30
	v_exp_f32_e32 v17, v17
	v_cvt_pk_bf16_f32 v16, v24, v16
	v_add_f32_e32 v20, 1.0, v20
	v_rcp_f32_e32 v20, v20
	v_add_f32_e32 v17, 1.0, v17
	v_rcp_f32_e32 v17, v17
	v_mul_f32_e32 v20, v22, v20
	v_mul_f32_e32 v22, v20, v18
	v_mul_f32_e32 v18, 0xbfb8aa3b, v31
	v_exp_f32_e32 v18, v18
	v_mul_f32_e32 v20, 0xbfb8aa3b, v23
	v_exp_f32_e32 v20, v20
	v_mul_f32_e32 v17, v30, v17
	v_add_f32_e32 v18, 1.0, v18
	v_rcp_f32_e32 v18, v18
	v_add_f32_e32 v20, 1.0, v20
	v_rcp_f32_e32 v20, v20
	v_mul_f32_e32 v17, v17, v26
	v_mul_f32_e32 v18, v31, v18
	v_mul_f32_e32 v18, v18, v27
	v_mul_f32_e32 v20, v23, v20
	v_mul_f32_e32 v19, v20, v19
	v_cvt_pk_bf16_f32 v17, v17, v18
	v_cvt_pk_bf16_f32 v18, v28, v25
	v_lshl_add_u64 v[20:21], v[32:33], 0, v[112:113]
	v_cvt_pk_bf16_f32 v19, v22, v19
	s_nop 0
	global_store_dwordx4 v[20:21], v[16:19], off sc1 nt
	s_nop 1
	v_mul_f32_e32 v18, 0xbfb8aa3b, v12
	v_exp_f32_e32 v18, v18
	v_add_u32_e32 v16, 0xb0, v158
	v_mad_i64_i32 v[16:17], s[28:29], v16, s91, v[138:139]
	v_add_f32_e32 v18, 1.0, v18
	v_rcp_f32_e32 v18, v18
	s_nop 0
	v_mul_f32_e32 v12, v12, v18
	v_mul_f32_e32 v8, v12, v8
	v_mul_f32_e32 v12, 0xbfb8aa3b, v4
	v_exp_f32_e32 v12, v12
	s_nop 0
	v_add_f32_e32 v12, 1.0, v12
	v_rcp_f32_e32 v12, v12
	s_nop 0
	v_mul_f32_e32 v4, v4, v12
	v_mul_f32_e32 v12, v4, v0
	v_mul_f32_e32 v0, 0xbfb8aa3b, v13
	v_mul_f32_e32 v4, 0xbfb8aa3b, v5
	v_exp_f32_e32 v0, v0
	v_exp_f32_e32 v4, v4
	v_add_f32_e32 v0, 1.0, v0
	v_add_f32_e32 v4, 1.0, v4
	v_rcp_f32_e32 v0, v0
	v_rcp_f32_e32 v4, v4
	v_mul_f32_e32 v0, v13, v0
	v_mul_f32_e32 v4, v5, v4
	v_mul_f32_e32 v0, v0, v9
	v_mul_f32_e32 v9, v4, v1
	v_mul_f32_e32 v4, 0xbfb8aa3b, v6
	v_exp_f32_e32 v4, v4
	v_mul_f32_e32 v1, 0xbfb8aa3b, v14
	v_exp_f32_e32 v1, v1
	v_cvt_pk_bf16_f32 v0, v8, v0
	v_add_f32_e32 v4, 1.0, v4
	v_rcp_f32_e32 v4, v4
	v_add_f32_e32 v1, 1.0, v1
	v_rcp_f32_e32 v1, v1
	v_mul_f32_e32 v4, v6, v4
	v_mul_f32_e32 v6, v4, v2
	v_mul_f32_e32 v2, 0xbfb8aa3b, v15
	v_mul_f32_e32 v4, 0xbfb8aa3b, v7
	v_exp_f32_e32 v2, v2
	v_exp_f32_e32 v4, v4
	v_mul_f32_e32 v1, v14, v1
	v_mul_f32_e32 v1, v1, v10
	v_add_f32_e32 v2, 1.0, v2
	v_add_f32_e32 v4, 1.0, v4
	v_rcp_f32_e32 v2, v2
	v_rcp_f32_e32 v4, v4
	v_mul_f32_e32 v2, v15, v2
	v_mul_f32_e32 v4, v7, v4
	v_mul_f32_e32 v2, v2, v11
	v_mul_f32_e32 v3, v4, v3
	v_lshl_add_u64 v[4:5], v[16:17], 0, v[112:113]
	v_cvt_pk_bf16_f32 v1, v1, v2
	v_cvt_pk_bf16_f32 v2, v12, v9
	v_cvt_pk_bf16_f32 v3, v6, v3
	s_nop 0
	global_store_dwordx4 v[4:5], v[0:3], off sc1 nt
	s_nop 1
	s_cbranch_vccnz .LBB0_176
	s_andn2_b64 vcc, exec, s[38:39]
	s_cbranch_vccnz .LBB0_175
	s_barrier
	s_branch .LBB0_175
